# MT0 neighbourhood-attention latent tile loop rewritten by hand (C-init reference, sum-based pow2 rescale, fully-masked key groups skipped per wave type)
# speedup vs baseline: 1.0335x; 1.0036x over previous
.LBB0_876:
	v_lshlrev_b32_e32 v11, 3, v15
	v_add_u32_e32 v15, s8, v161
	v_mov_b64_e32 v[16:17], s[0:1]
	v_mad_i64_i32 v[16:17], s[4:5], v15, s33, v[16:17]
	v_add_u32_e32 v15, s8, v163
	v_mov_b64_e32 v[18:19], s[2:3]
	v_lshl_add_u64 v[16:17], v[8:9], 1, v[16:17]
	v_mad_i64_i32 v[18:19], s[4:5], v15, s33, v[18:19]
	v_lshlrev_b32_e32 v184, 1, v11
	v_lshl_add_u64 v[18:19], v[18:19], 0, v[184:185]
	global_load_dwordx4 v[112:115], v[16:17], off
	global_load_dwordx4 v[116:119], v[18:19], off
	v_mul_lo_u32 v11, v161, s81
	v_add_u32_e32 v11, 0, v11
	v_lshlrev_b32_e32 v14, 4, v14
	v_add_u32_e32 v171, v11, v14
	s_waitcnt vmcnt(3)
	ds_write_b128 v171, v[4:7]
	v_mul_lo_u32 v4, v163, s80
	v_add_u32_e32 v4, 0, v4
	v_add_u32_e32 v172, v4, v10
	s_waitcnt vmcnt(2)
	ds_write_b128 v172, v[0:3] offset:26624
	s_waitcnt lgkmcnt(0)
	s_barrier
	s_cmp_lt_i32 s25, -15
	s_cbranch_scc1 .LBB0_1034
	v_lshl_add_u64 v[164:165], v[8:9], 1, s[0:1]
	v_readlane_b32 s0, v255, 3
	s_add_i32 s7, s7, s0
	v_readlane_b32 s0, v254, 17
	v_lshlrev_b32_e32 v1, 2, v169
	v_lshrrev_b32_e32 v2, 2, v12
	v_or_b32_e32 v0, s0, v13
	v_sub_u32_e64 v0, v0, 8 clamp
	s_max_i32 s0, s7, 4
	v_min_u32_e32 v0, 48, v0
	s_add_i32 s0, s0, -4
	v_and_b32_e32 v3, 16, v12
	v_lshlrev_b32_e32 v4, 2, v13
	s_min_u32 s39, s0, 24
	v_and_or_b32 v2, v2, 3, v1
	v_and_or_b32 v3, v4, 12, v3
	v_cmp_ge_u32_e64 s[0:1], v1, v0
	v_lshlrev_b32_e32 v174, 1, v3
	v_add_u32_e32 v3, 16, v0
	v_mad_u32_u24 v175, v2, s80, 0
	v_or_b32_e32 v2, 32, v1
	v_writelane_b32 v255, s0, 31
	v_cmp_ge_u32_e32 vcc, v2, v0
	v_or_b32_e32 v5, 33, v1
	v_writelane_b32 v255, s1, 32
	v_cmp_lt_u32_e64 s[0:1], v2, v3
	v_or_b32_e32 v2, 1, v1
	s_and_b64 s[42:43], vcc, s[0:1]
	v_cmp_lt_u32_e64 s[0:1], v2, v0
	v_cmp_ge_u32_e32 vcc, v5, v0
	v_mad_u32_u24 v173, v13, s81, 0
	v_writelane_b32 v255, s0, 33
	v_cmp_lt_u32_e64 s[40:41], v1, v0
	s_add_i32 s34, s25, 15
	v_writelane_b32 v255, s1, 34
	v_cmp_ge_u32_e64 s[0:1], v2, v0
	v_or_b32_e32 v2, 2, v1
	v_cmp_ge_u32_e64 s[52:53], v2, v0
	v_writelane_b32 v255, s0, 35
	s_add_i32 s38, s25, 16
	s_sub_i32 s46, -12, s25
	v_writelane_b32 v255, s1, 36
	v_cmp_lt_u32_e64 s[0:1], v5, v3
	s_and_b64 s[48:49], vcc, s[0:1]
	v_cmp_lt_u32_e64 s[0:1], v2, v0
	v_or_b32_e32 v5, 34, v1
	v_cmp_ge_u32_e32 vcc, v5, v0
	v_writelane_b32 v255, s0, 37
	v_or_b32_e32 v2, 3, v1
	v_cmp_lt_u32_e64 s[56:57], v2, v0
	v_writelane_b32 v255, s1, 38
	v_cmp_lt_u32_e64 s[0:1], v5, v3
	v_or_b32_e32 v5, 35, v1
	s_and_b64 s[54:55], vcc, s[0:1]
	v_cmp_ge_u32_e64 s[58:59], v2, v0
	v_cmp_ge_u32_e32 vcc, v5, v0
	v_cmp_lt_u32_e64 s[0:1], v5, v3
	v_or_b32_e32 v2, 8, v1
	v_or_b32_e32 v5, 40, v1
	s_and_b64 s[60:61], vcc, s[0:1]
	v_cmp_lt_u32_e64 s[62:63], v2, v0
	v_cmp_ge_u32_e64 s[64:65], v2, v0
	v_cmp_ge_u32_e32 vcc, v5, v0
	v_cmp_lt_u32_e64 s[0:1], v5, v3
	v_or_b32_e32 v2, 9, v1
	v_or_b32_e32 v5, 41, v1
	s_and_b64 s[66:67], vcc, s[0:1]
	v_cmp_lt_u32_e64 s[68:69], v2, v0
	v_cmp_ge_u32_e64 s[70:71], v2, v0
	v_cmp_ge_u32_e32 vcc, v5, v0
	v_cmp_lt_u32_e64 s[0:1], v5, v3
	v_or_b32_e32 v2, 10, v1
	v_or_b32_e32 v5, 42, v1
	s_and_b64 s[72:73], vcc, s[0:1]
	v_cmp_lt_u32_e64 s[74:75], v2, v0
	v_cmp_ge_u32_e64 s[76:77], v2, v0
	v_cmp_ge_u32_e32 vcc, v5, v0
	v_cmp_lt_u32_e64 s[0:1], v5, v3
	v_or_b32_e32 v2, 11, v1
	v_or_b32_e32 v5, 43, v1
	s_and_b64 s[78:79], vcc, s[0:1]
	v_cmp_lt_u32_e64 s[80:81], v2, v0
	v_cmp_ge_u32_e64 s[82:83], v2, v0
	v_cmp_ge_u32_e32 vcc, v5, v0
	v_cmp_lt_u32_e64 s[0:1], v5, v3
	v_or_b32_e32 v2, 16, v1
	s_and_b64 s[84:85], vcc, s[0:1]
	v_cmp_ge_u32_e32 vcc, v2, v0
	v_or_b32_e32 v2, 17, v1
	s_and_b64 s[86:87], vcc, s[40:41]
	v_cmp_ge_u32_e32 vcc, v2, v0
	v_cmp_lt_u32_e64 s[0:1], v2, v3
	v_or_b32_e32 v2, 18, v1
	s_and_b64 s[90:91], vcc, s[0:1]
	v_cmp_ge_u32_e32 vcc, v2, v0
	v_cmp_lt_u32_e64 s[0:1], v2, v3
	v_or_b32_e32 v2, 19, v1
	v_or_b32_e32 v5, 48, v1
	s_and_b64 s[94:95], vcc, s[0:1]
	v_cmp_ge_u32_e32 vcc, v2, v0
	v_cmp_lt_u32_e64 s[0:1], v2, v3
	v_or_b32_e32 v2, 24, v1
	v_cmp_lt_u32_e64 s[88:89], v5, v3
	v_or_b32_e32 v5, 49, v1
	s_and_b64 s[0:1], vcc, s[0:1]
	v_cmp_ge_u32_e32 vcc, v2, v0
	v_cmp_lt_u32_e64 s[4:5], v2, v3
	v_or_b32_e32 v2, 25, v1
	v_cmp_lt_u32_e64 s[92:93], v5, v3
	v_or_b32_e32 v5, 50, v1
	s_and_b64 s[4:5], vcc, s[4:5]
	v_cmp_ge_u32_e32 vcc, v2, v0
	v_cmp_lt_u32_e64 s[8:9], v2, v3
	v_or_b32_e32 v2, 26, v1
	v_cmp_lt_u32_e64 s[96:97], v5, v3
	v_or_b32_e32 v5, 51, v1
	s_and_b64 s[8:9], vcc, s[8:9]
	v_cmp_ge_u32_e32 vcc, v2, v0
	v_cmp_lt_u32_e64 s[12:13], v2, v3
	v_or_b32_e32 v2, 27, v1
	s_mul_i32 s25, s20, 0x7c
	v_lshl_add_u64 v[166:167], s[2:3], 0, v[184:185]
	v_cmp_lt_u32_e64 s[2:3], v5, v3
	v_or_b32_e32 v5, 56, v1
	s_and_b64 s[12:13], vcc, s[12:13]
	v_cmp_ge_u32_e32 vcc, v2, v0
	v_add_u32_e32 v0, s25, v162
	s_lshl_b32 s44, s6, 8
	v_cmp_lt_u32_e64 s[6:7], v5, v3
	v_or_b32_e32 v5, 57, v1
	v_sub_u32_e32 v0, v0, v4
	s_mulk_i32 s24, 0x1f0
	v_cmp_lt_u32_e64 s[10:11], v5, v3
	v_or_b32_e32 v5, 58, v1
	v_or_b32_e32 v1, 59, v1
	v_cmp_lt_u32_e64 s[16:17], v2, v3
	v_subrev_u32_e32 v0, s24, v0
	v_readlane_b32 s24, v255, 5
	v_mov_b32_e32 v176, 0
	s_add_i32 s44, s44, 0x8000
	s_add_i32 s45, s39, 8
	v_cmp_lt_u32_e64 s[14:15], v5, v3
	s_and_b64 s[16:17], vcc, s[16:17]
	v_cmp_lt_u32_e64 s[18:19], v1, v3
	v_add_u32_e32 v177, s24, v0
	v_mov_b32_e32 v168, 0xf149f2ca
	s_mov_b32 s47, 0
	v_mov_b32_e32 v16, 0
	v_mov_b32_e32 v17, v176
	v_mov_b32_e32 v18, v176
	v_mov_b32_e32 v19, v176
	v_mov_b32_e32 v20, v176
	v_mov_b32_e32 v21, v176
	v_mov_b32_e32 v22, v176
	v_mov_b32_e32 v23, v176
	v_mov_b32_e32 v24, v176
	v_mov_b32_e32 v25, v176
	v_mov_b32_e32 v26, v176
	v_mov_b32_e32 v27, v176
	v_mov_b32_e32 v28, v176
	v_mov_b32_e32 v29, v176
	v_mov_b32_e32 v30, v176
	v_mov_b32_e32 v31, v176
	v_mov_b32_e32 v0, v176
	v_mov_b32_e32 v1, v176
	v_mov_b32_e32 v2, v176
	v_mov_b32_e32 v3, v176
	v_mov_b32_e32 v4, v176
	v_mov_b32_e32 v5, v176
	v_mov_b32_e32 v6, v176
	v_mov_b32_e32 v7, v176
	v_mov_b32_e32 v8, v176
	v_mov_b32_e32 v9, v176
	v_mov_b32_e32 v10, v176
	v_mov_b32_e32 v11, v176
	v_mov_b32_e32 v12, v176
	v_mov_b32_e32 v13, v176
	v_mov_b32_e32 v14, v176
	v_mov_b32_e32 v15, v176
	v_mov_b32_e32 v168, 0
	v_readlane_b32 s51, v254, 17
	v_mov_b32_e32 v218, 0
	v_mov_b32_e32 v219, 0
	v_mov_b32_e32 v220, 0
	v_mov_b32_e32 v221, 0
	v_mov_b32_e32 v222, 0
	v_mov_b32_e32 v223, 0
	v_mov_b32_e32 v224, 0
	v_mov_b32_e32 v225, 0
	v_mov_b32_e32 v226, 0
	v_mov_b32_e32 v227, 0
	v_mov_b32_e32 v228, 0
	v_mov_b32_e32 v229, 0
	v_mov_b32_e32 v230, 0
	v_mov_b32_e32 v231, 0
	v_mov_b32_e32 v232, 0
	v_mov_b32_e32 v233, 0
.LBB0_878:
	s_add_i32 s24, s47, 2
	s_min_i32 s24, s24, s34
	s_cmp_lt_i32 s24, s35
	s_cselect_b32 s25, s21, s46
	s_cselect_b32 s26, s29, s44
	s_add_i32 s25, s25, s24
	s_lshl_b32 s25, s25, 6
	s_add_i32 s26, s26, s25
	v_add_u32_e32 v236, s26, v161
	v_mad_i64_i32 v[236:237], s[98:99], v236, s33, v[164:165]
	global_load_dwordx4 v[120:123], v[236:237], off
	v_add_u32_e32 v236, s26, v163
	v_mad_i64_i32 v[236:237], s[98:99], v236, s33, v[166:167]
	global_load_dwordx4 v[124:127], v[236:237], off
	s_mov_b32 s24, s47
	s_cmp_ge_i32 s24, s35
	s_cbranch_scc1 .Lm0_ctxA
	s_add_i32 s25, s20, s24
	s_add_i32 s25, s25, -4
	s_cmp_lt_u32 s25, s39
	s_cbranch_scc1 .Lm0_doneA
	s_cmp_ge_u32 s25, s45
	s_cbranch_scc1 .Lm0_doneA
	s_cmp_lg_u32 s51, 0
	s_cbranch_scc1 .Lm0_m1A
	v_add_u32_e32 v236, v173, v162
	ds_read_b128 v[128:131], v236
	ds_read_b128 v[144:147], v236 offset:6656
	ds_read_b128 v[132:135], v236 offset:32
	ds_read_b128 v[148:151], v236 offset:6688
	ds_read_b128 v[136:139], v236 offset:64
	ds_read_b128 v[152:155], v236 offset:6720
	ds_read_b128 v[140:143], v236 offset:96
	ds_read_b128 v[156:159], v236 offset:6752
	v_add_u32_e32 v237, v175, v174
	s_waitcnt lgkmcnt(7)
	v_mfma_f32_32x32x16_bf16 v[32:47], v[128:131], v[96:99], v[218:233]
	s_waitcnt lgkmcnt(6)
	v_mfma_f32_32x32x16_bf16 v[48:63], v[144:147], v[96:99], v[218:233]
	s_waitcnt lgkmcnt(5)
	v_mfma_f32_32x32x16_bf16 v[32:47], v[132:135], v[100:103], v[32:47]
	s_waitcnt lgkmcnt(4)
	v_mfma_f32_32x32x16_bf16 v[48:63], v[148:151], v[100:103], v[48:63]
	s_waitcnt lgkmcnt(3)
	v_mfma_f32_32x32x16_bf16 v[32:47], v[136:139], v[104:107], v[32:47]
	s_waitcnt lgkmcnt(2)
	v_mfma_f32_32x32x16_bf16 v[48:63], v[152:155], v[104:107], v[48:63]
	s_waitcnt lgkmcnt(1)
	v_mfma_f32_32x32x16_bf16 v[32:47], v[140:143], v[108:111], v[32:47]
	s_waitcnt lgkmcnt(0)
	v_mfma_f32_32x32x16_bf16 v[48:63], v[156:159], v[108:111], v[48:63]
	ds_read_b32 v64, v177 offset:0
	ds_read_b32 v65, v177 offset:4
	ds_read_b32 v66, v177 offset:8
	ds_read_b32 v67, v177 offset:12
	ds_read_b32 v68, v177 offset:32
	ds_read_b32 v69, v177 offset:36
	ds_read_b32 v70, v177 offset:40
	ds_read_b32 v71, v177 offset:44
	ds_read_b32 v72, v177 offset:64
	ds_read_b32 v73, v177 offset:68
	ds_read_b32 v74, v177 offset:72
	ds_read_b32 v75, v177 offset:76
	ds_read_b32 v76, v177 offset:96
	ds_read_b32 v77, v177 offset:100
	ds_read_b32 v78, v177 offset:104
	ds_read_b32 v79, v177 offset:108
	ds_read_b32 v80, v177 offset:128
	ds_read_b32 v81, v177 offset:132
	ds_read_b32 v82, v177 offset:136
	ds_read_b32 v83, v177 offset:140
	ds_read_b32 v84, v177 offset:160
	ds_read_b32 v85, v177 offset:164
	ds_read_b32 v86, v177 offset:168
	ds_read_b32 v87, v177 offset:172
	ds_read_b64_tr_b16 v[186:187], v237 offset:26624
	ds_read_b64_tr_b16 v[188:189], v237 offset:28160
	ds_read_b64_tr_b16 v[190:191], v237 offset:26688
	ds_read_b64_tr_b16 v[192:193], v237 offset:28224
	ds_read_b64_tr_b16 v[194:195], v237 offset:29696
	ds_read_b64_tr_b16 v[196:197], v237 offset:31232
	ds_read_b64_tr_b16 v[198:199], v237 offset:29760
	ds_read_b64_tr_b16 v[200:201], v237 offset:31296
	ds_read_b64_tr_b16 v[202:203], v237 offset:32768
	ds_read_b64_tr_b16 v[204:205], v237 offset:34304
	ds_read_b64_tr_b16 v[206:207], v237 offset:32832
	ds_read_b64_tr_b16 v[208:209], v237 offset:34368
	v_readlane_b32 s24, v255, 33
	v_readlane_b32 s25, v255, 34
	v_readlane_b32 s26, v255, 37
	v_readlane_b32 s27, v255, 38
	s_waitcnt lgkmcnt(12)
	v_fmac_f32_e32 v64, 0x3e38aa3b, v32
	v_fmac_f32_e32 v65, 0x3e38aa3b, v33
	v_fmac_f32_e32 v66, 0x3e38aa3b, v34
	v_fmac_f32_e32 v67, 0x3e38aa3b, v35
	v_fmac_f32_e32 v68, 0x3e38aa3b, v36
	v_fmac_f32_e32 v69, 0x3e38aa3b, v37
	v_fmac_f32_e32 v70, 0x3e38aa3b, v38
	v_fmac_f32_e32 v71, 0x3e38aa3b, v39
	v_cndmask_b32_e64 v64, v64, v238, s[40:41]
	v_cndmask_b32_e64 v65, v65, v238, s[24:25]
	v_cndmask_b32_e64 v66, v66, v238, s[26:27]
	v_cndmask_b32_e64 v67, v67, v238, s[56:57]
	v_cndmask_b32_e64 v68, v68, v238, s[62:63]
	v_cndmask_b32_e64 v69, v69, v238, s[68:69]
	v_cndmask_b32_e64 v70, v70, v238, s[74:75]
	v_cndmask_b32_e64 v71, v71, v238, s[80:81]
	v_exp_f32_e32 v64, v64
	v_exp_f32_e32 v65, v65
	v_exp_f32_e32 v66, v66
	v_exp_f32_e32 v67, v67
	v_exp_f32_e32 v68, v68
	v_exp_f32_e32 v69, v69
	v_exp_f32_e32 v70, v70
	v_exp_f32_e32 v71, v71
	v_add_f32_e32 v234, v64, v66
	v_add_f32_e32 v235, v65, v67
	v_add_f32_e32 v234, v234, v68
	v_add_f32_e32 v235, v235, v69
	v_add_f32_e32 v234, v234, v70
	v_add_f32_e32 v235, v235, v71
	v_cvt_pk_bf16_f32 v64, v64, v65
	v_cvt_pk_bf16_f32 v65, v66, v67
	v_cvt_pk_bf16_f32 v66, v68, v69
	v_cvt_pk_bf16_f32 v67, v70, v71
	v_fmac_f32_e32 v72, 0x3e38aa3b, v40
	v_fmac_f32_e32 v73, 0x3e38aa3b, v41
	s_waitcnt lgkmcnt(10)
	v_mfma_f32_32x32x16_bf16 v[16:31], v[186:189], v[64:67], v[16:31]
	v_fmac_f32_e32 v74, 0x3e38aa3b, v42
	v_fmac_f32_e32 v75, 0x3e38aa3b, v43
	v_fmac_f32_e32 v76, 0x3e38aa3b, v44
	v_fmac_f32_e32 v77, 0x3e38aa3b, v45
	v_fmac_f32_e32 v78, 0x3e38aa3b, v46
	v_fmac_f32_e32 v79, 0x3e38aa3b, v47
	s_waitcnt lgkmcnt(8)
	v_mfma_f32_32x32x16_bf16 v[0:15], v[190:193], v[64:67], v[0:15]
	v_cndmask_b32_e64 v72, v238, v72, s[86:87]
	v_cndmask_b32_e64 v73, v238, v73, s[90:91]
	v_cndmask_b32_e64 v74, v238, v74, s[94:95]
	v_cndmask_b32_e64 v75, v238, v75, s[0:1]
	v_cndmask_b32_e64 v76, v238, v76, s[4:5]
	v_cndmask_b32_e64 v77, v238, v77, s[8:9]
	v_cndmask_b32_e64 v78, v238, v78, s[12:13]
	v_cndmask_b32_e64 v79, v238, v79, s[16:17]
	v_exp_f32_e32 v72, v72
	v_exp_f32_e32 v73, v73
	v_exp_f32_e32 v74, v74
	v_exp_f32_e32 v75, v75
	v_exp_f32_e32 v76, v76
	v_exp_f32_e32 v77, v77
	v_exp_f32_e32 v78, v78
	v_exp_f32_e32 v79, v79
	v_add_f32_e32 v234, v234, v72
	v_add_f32_e32 v235, v235, v73
	v_add_f32_e32 v234, v234, v74
	v_add_f32_e32 v235, v235, v75
	v_add_f32_e32 v234, v234, v76
	v_add_f32_e32 v235, v235, v77
	v_add_f32_e32 v234, v234, v78
	v_add_f32_e32 v235, v235, v79
	v_cvt_pk_bf16_f32 v72, v72, v73
	v_cvt_pk_bf16_f32 v73, v74, v75
	v_cvt_pk_bf16_f32 v74, v76, v77
	v_cvt_pk_bf16_f32 v75, v78, v79
	v_fmac_f32_e32 v80, 0x3e38aa3b, v48
	v_fmac_f32_e32 v81, 0x3e38aa3b, v49
	s_waitcnt lgkmcnt(6)
	v_mfma_f32_32x32x16_bf16 v[16:31], v[194:197], v[72:75], v[16:31]
	v_fmac_f32_e32 v82, 0x3e38aa3b, v50
	v_fmac_f32_e32 v83, 0x3e38aa3b, v51
	v_fmac_f32_e32 v84, 0x3e38aa3b, v52
	v_fmac_f32_e32 v85, 0x3e38aa3b, v53
	v_fmac_f32_e32 v86, 0x3e38aa3b, v54
	v_fmac_f32_e32 v87, 0x3e38aa3b, v55
	s_waitcnt lgkmcnt(4)
	v_mfma_f32_32x32x16_bf16 v[0:15], v[198:201], v[72:75], v[0:15]
	v_cndmask_b32_e64 v80, v238, v80, s[42:43]
	v_cndmask_b32_e64 v81, v238, v81, s[48:49]
	v_cndmask_b32_e64 v82, v238, v82, s[54:55]
	v_cndmask_b32_e64 v83, v238, v83, s[60:61]
	v_cndmask_b32_e64 v84, v238, v84, s[66:67]
	v_cndmask_b32_e64 v85, v238, v85, s[72:73]
	v_cndmask_b32_e64 v86, v238, v86, s[78:79]
	v_cndmask_b32_e64 v87, v238, v87, s[84:85]
	v_exp_f32_e32 v80, v80
	v_exp_f32_e32 v81, v81
	v_exp_f32_e32 v82, v82
	v_exp_f32_e32 v83, v83
	v_exp_f32_e32 v84, v84
	v_exp_f32_e32 v85, v85
	v_exp_f32_e32 v86, v86
	v_exp_f32_e32 v87, v87
	v_add_f32_e32 v234, v234, v80
	v_add_f32_e32 v235, v235, v81
	v_add_f32_e32 v234, v234, v82
	v_add_f32_e32 v235, v235, v83
	v_add_f32_e32 v234, v234, v84
	v_add_f32_e32 v235, v235, v85
	v_add_f32_e32 v234, v234, v86
	v_add_f32_e32 v235, v235, v87
	v_cvt_pk_bf16_f32 v80, v80, v81
	v_cvt_pk_bf16_f32 v81, v82, v83
	v_cvt_pk_bf16_f32 v82, v84, v85
	v_cvt_pk_bf16_f32 v83, v86, v87
	s_nop 1
	s_waitcnt lgkmcnt(2)
	v_mfma_f32_32x32x16_bf16 v[16:31], v[202:205], v[80:83], v[16:31]
	s_waitcnt lgkmcnt(0)
	v_mfma_f32_32x32x16_bf16 v[0:15], v[206:209], v[80:83], v[0:15]
	v_add_f32_e32 v234, v234, v235
	v_add_f32_e32 v176, v176, v234
	v_cmp_lt_f32_e32 vcc, 0x43000000, v234
	s_cbranch_vccz .Lm0_nr_m0A
	s_nop 15
	v_mov_b32_e32 v235, v234
	s_nop 1
	v_permlane32_swap_b32_e32 v234, v235
	v_add_f32_e32 v178, v234, v235
	v_cmp_lt_f32_e32 vcc, 0x43800000, v178
	v_frexp_exp_i32_f32_e32 v179, v178
	s_nop 1
	v_cndmask_b32_e32 v179, 0, v179, vcc
	v_cvt_f32_i32_e32 v180, v179
	v_sub_u32_e32 v179, 0, v179
	v_ldexp_f32 v178, 1.0, v179
	v_add_f32_e32 v168, v168, v180
	v_mul_f32_e32 v176, v176, v178
	v_mul_f32_e32 v0, v0, v178
	v_mul_f32_e32 v1, v1, v178
	v_mul_f32_e32 v2, v2, v178
	v_mul_f32_e32 v3, v3, v178
	v_mul_f32_e32 v4, v4, v178
	v_mul_f32_e32 v5, v5, v178
	v_mul_f32_e32 v6, v6, v178
	v_mul_f32_e32 v7, v7, v178
	v_mul_f32_e32 v8, v8, v178
	v_mul_f32_e32 v9, v9, v178
	v_mul_f32_e32 v10, v10, v178
	v_mul_f32_e32 v11, v11, v178
	v_mul_f32_e32 v12, v12, v178
	v_mul_f32_e32 v13, v13, v178
	v_mul_f32_e32 v14, v14, v178
	v_mul_f32_e32 v15, v15, v178
	v_mul_f32_e32 v16, v16, v178
	v_mul_f32_e32 v17, v17, v178
	v_mul_f32_e32 v18, v18, v178
	v_mul_f32_e32 v19, v19, v178
	v_mul_f32_e32 v20, v20, v178
	v_mul_f32_e32 v21, v21, v178
	v_mul_f32_e32 v22, v22, v178
	v_mul_f32_e32 v23, v23, v178
	v_mul_f32_e32 v24, v24, v178
	v_mul_f32_e32 v25, v25, v178
	v_mul_f32_e32 v26, v26, v178
	v_mul_f32_e32 v27, v27, v178
	v_mul_f32_e32 v28, v28, v178
	v_mul_f32_e32 v29, v29, v178
	v_mul_f32_e32 v30, v30, v178
	v_mul_f32_e32 v31, v31, v178
	v_mul_f32_e32 v218, 0xc0b17218, v168
	v_mov_b32_e32 v219, v218
	v_mov_b32_e32 v220, v218
	v_mov_b32_e32 v221, v218
	v_mov_b32_e32 v222, v218
	v_mov_b32_e32 v223, v218
	v_mov_b32_e32 v224, v218
	v_mov_b32_e32 v225, v218
	v_mov_b32_e32 v226, v218
	v_mov_b32_e32 v227, v218
	v_mov_b32_e32 v228, v218
	v_mov_b32_e32 v229, v218
	v_mov_b32_e32 v230, v218
	v_mov_b32_e32 v231, v218
	v_mov_b32_e32 v232, v218
	v_mov_b32_e32 v233, v218

.Lm0_m1A:
	v_add_u32_e32 v236, v173, v162
	ds_read_b128 v[128:131], v236
	ds_read_b128 v[144:147], v236 offset:6656
	ds_read_b128 v[132:135], v236 offset:32
	ds_read_b128 v[148:151], v236 offset:6688
	ds_read_b128 v[136:139], v236 offset:64
	ds_read_b128 v[152:155], v236 offset:6720
	ds_read_b128 v[140:143], v236 offset:96
	ds_read_b128 v[156:159], v236 offset:6752
	v_add_u32_e32 v237, v175, v174
	s_waitcnt lgkmcnt(7)
	v_mfma_f32_32x32x16_bf16 v[32:47], v[128:131], v[96:99], v[218:233]
	s_waitcnt lgkmcnt(6)
	v_mfma_f32_32x32x16_bf16 v[48:63], v[144:147], v[96:99], v[218:233]
	s_waitcnt lgkmcnt(5)
	v_mfma_f32_32x32x16_bf16 v[32:47], v[132:135], v[100:103], v[32:47]
	s_waitcnt lgkmcnt(4)
	v_mfma_f32_32x32x16_bf16 v[48:63], v[148:151], v[100:103], v[48:63]
	s_waitcnt lgkmcnt(3)
	v_mfma_f32_32x32x16_bf16 v[32:47], v[136:139], v[104:107], v[32:47]
	s_waitcnt lgkmcnt(2)
	v_mfma_f32_32x32x16_bf16 v[48:63], v[152:155], v[104:107], v[48:63]
	s_waitcnt lgkmcnt(1)
	v_mfma_f32_32x32x16_bf16 v[32:47], v[140:143], v[108:111], v[32:47]
	s_waitcnt lgkmcnt(0)
	v_mfma_f32_32x32x16_bf16 v[48:63], v[156:159], v[108:111], v[48:63]
	ds_read_b32 v72, v177 offset:64
	ds_read_b32 v73, v177 offset:68
	ds_read_b32 v74, v177 offset:72
	ds_read_b32 v75, v177 offset:76
	ds_read_b32 v76, v177 offset:96
	ds_read_b32 v77, v177 offset:100
	ds_read_b32 v78, v177 offset:104
	ds_read_b32 v79, v177 offset:108
	ds_read_b32 v80, v177 offset:128
	ds_read_b32 v81, v177 offset:132
	ds_read_b32 v82, v177 offset:136
	ds_read_b32 v83, v177 offset:140
	ds_read_b32 v84, v177 offset:160
	ds_read_b32 v85, v177 offset:164
	ds_read_b32 v86, v177 offset:168
	ds_read_b32 v87, v177 offset:172
	ds_read_b32 v88, v177 offset:192
	ds_read_b32 v89, v177 offset:196
	ds_read_b32 v90, v177 offset:200
	ds_read_b32 v91, v177 offset:204
	ds_read_b32 v92, v177 offset:224
	ds_read_b32 v93, v177 offset:228
	ds_read_b32 v94, v177 offset:232
	ds_read_b32 v95, v177 offset:236
	ds_read_b64_tr_b16 v[186:187], v237 offset:29696
	ds_read_b64_tr_b16 v[188:189], v237 offset:31232
	ds_read_b64_tr_b16 v[190:191], v237 offset:29760
	ds_read_b64_tr_b16 v[192:193], v237 offset:31296
	ds_read_b64_tr_b16 v[194:195], v237 offset:32768
	ds_read_b64_tr_b16 v[196:197], v237 offset:34304
	ds_read_b64_tr_b16 v[198:199], v237 offset:32832
	ds_read_b64_tr_b16 v[200:201], v237 offset:34368
	ds_read_b64_tr_b16 v[202:203], v237 offset:35840
	ds_read_b64_tr_b16 v[204:205], v237 offset:37376
	ds_read_b64_tr_b16 v[206:207], v237 offset:35904
	ds_read_b64_tr_b16 v[208:209], v237 offset:37440
	s_waitcnt lgkmcnt(12)
	v_fmac_f32_e32 v72, 0x3e38aa3b, v40
	v_fmac_f32_e32 v73, 0x3e38aa3b, v41
	v_fmac_f32_e32 v74, 0x3e38aa3b, v42
	v_fmac_f32_e32 v75, 0x3e38aa3b, v43
	v_fmac_f32_e32 v76, 0x3e38aa3b, v44
	v_fmac_f32_e32 v77, 0x3e38aa3b, v45
	v_fmac_f32_e32 v78, 0x3e38aa3b, v46
	v_fmac_f32_e32 v79, 0x3e38aa3b, v47
	v_cndmask_b32_e64 v72, v238, v72, s[86:87]
	v_cndmask_b32_e64 v73, v238, v73, s[90:91]
	v_cndmask_b32_e64 v74, v238, v74, s[94:95]
	v_cndmask_b32_e64 v75, v238, v75, s[0:1]
	v_cndmask_b32_e64 v76, v238, v76, s[4:5]
	v_cndmask_b32_e64 v77, v238, v77, s[8:9]
	v_cndmask_b32_e64 v78, v238, v78, s[12:13]
	v_cndmask_b32_e64 v79, v238, v79, s[16:17]
	v_exp_f32_e32 v72, v72
	v_exp_f32_e32 v73, v73
	v_exp_f32_e32 v74, v74
	v_exp_f32_e32 v75, v75
	v_exp_f32_e32 v76, v76
	v_exp_f32_e32 v77, v77
	v_exp_f32_e32 v78, v78
	v_exp_f32_e32 v79, v79
	v_add_f32_e32 v234, v72, v74
	v_add_f32_e32 v235, v73, v75
	v_add_f32_e32 v234, v234, v76
	v_add_f32_e32 v235, v235, v77
	v_add_f32_e32 v234, v234, v78
	v_add_f32_e32 v235, v235, v79
	v_cvt_pk_bf16_f32 v72, v72, v73
	v_cvt_pk_bf16_f32 v73, v74, v75
	v_cvt_pk_bf16_f32 v74, v76, v77
	v_cvt_pk_bf16_f32 v75, v78, v79
	v_fmac_f32_e32 v80, 0x3e38aa3b, v48
	v_fmac_f32_e32 v81, 0x3e38aa3b, v49
	s_waitcnt lgkmcnt(10)
	v_mfma_f32_32x32x16_bf16 v[16:31], v[186:189], v[72:75], v[16:31]
	v_fmac_f32_e32 v82, 0x3e38aa3b, v50
	v_fmac_f32_e32 v83, 0x3e38aa3b, v51
	v_fmac_f32_e32 v84, 0x3e38aa3b, v52
	v_fmac_f32_e32 v85, 0x3e38aa3b, v53
	v_fmac_f32_e32 v86, 0x3e38aa3b, v54
	v_fmac_f32_e32 v87, 0x3e38aa3b, v55
	s_waitcnt lgkmcnt(8)
	v_mfma_f32_32x32x16_bf16 v[0:15], v[190:193], v[72:75], v[0:15]
	v_cndmask_b32_e64 v80, v238, v80, s[42:43]
	v_cndmask_b32_e64 v81, v238, v81, s[48:49]
	v_cndmask_b32_e64 v82, v238, v82, s[54:55]
	v_cndmask_b32_e64 v83, v238, v83, s[60:61]
	v_cndmask_b32_e64 v84, v238, v84, s[66:67]
	v_cndmask_b32_e64 v85, v238, v85, s[72:73]
	v_cndmask_b32_e64 v86, v238, v86, s[78:79]
	v_cndmask_b32_e64 v87, v238, v87, s[84:85]
	v_exp_f32_e32 v80, v80
	v_exp_f32_e32 v81, v81
	v_exp_f32_e32 v82, v82
	v_exp_f32_e32 v83, v83
	v_exp_f32_e32 v84, v84
	v_exp_f32_e32 v85, v85
	v_exp_f32_e32 v86, v86
	v_exp_f32_e32 v87, v87
	v_add_f32_e32 v234, v234, v80
	v_add_f32_e32 v235, v235, v81
	v_add_f32_e32 v234, v234, v82
	v_add_f32_e32 v235, v235, v83
	v_add_f32_e32 v234, v234, v84
	v_add_f32_e32 v235, v235, v85
	v_add_f32_e32 v234, v234, v86
	v_add_f32_e32 v235, v235, v87
	v_cvt_pk_bf16_f32 v80, v80, v81
	v_cvt_pk_bf16_f32 v81, v82, v83
	v_cvt_pk_bf16_f32 v82, v84, v85
	v_cvt_pk_bf16_f32 v83, v86, v87
	v_fmac_f32_e32 v88, 0x3e38aa3b, v56
	v_fmac_f32_e32 v89, 0x3e38aa3b, v57
	s_waitcnt lgkmcnt(6)
	v_mfma_f32_32x32x16_bf16 v[16:31], v[194:197], v[80:83], v[16:31]
	v_fmac_f32_e32 v90, 0x3e38aa3b, v58
	v_fmac_f32_e32 v91, 0x3e38aa3b, v59
	v_fmac_f32_e32 v92, 0x3e38aa3b, v60
	v_fmac_f32_e32 v93, 0x3e38aa3b, v61
	v_fmac_f32_e32 v94, 0x3e38aa3b, v62
	v_fmac_f32_e32 v95, 0x3e38aa3b, v63
	s_waitcnt lgkmcnt(4)
	v_mfma_f32_32x32x16_bf16 v[0:15], v[198:201], v[80:83], v[0:15]
	v_cndmask_b32_e64 v88, v238, v88, s[88:89]
	v_cndmask_b32_e64 v89, v238, v89, s[92:93]
	v_cndmask_b32_e64 v90, v238, v90, s[96:97]
	v_cndmask_b32_e64 v91, v238, v91, s[2:3]
	v_cndmask_b32_e64 v92, v238, v92, s[6:7]
	v_cndmask_b32_e64 v93, v238, v93, s[10:11]
	v_cndmask_b32_e64 v94, v238, v94, s[14:15]
	v_cndmask_b32_e64 v95, v238, v95, s[18:19]
	v_exp_f32_e32 v88, v88
	v_exp_f32_e32 v89, v89
	v_exp_f32_e32 v90, v90
	v_exp_f32_e32 v91, v91
	v_exp_f32_e32 v92, v92
	v_exp_f32_e32 v93, v93
	v_exp_f32_e32 v94, v94
	v_exp_f32_e32 v95, v95
	v_add_f32_e32 v234, v234, v88
	v_add_f32_e32 v235, v235, v89
	v_add_f32_e32 v234, v234, v90
	v_add_f32_e32 v235, v235, v91
	v_add_f32_e32 v234, v234, v92
	v_add_f32_e32 v235, v235, v93
	v_add_f32_e32 v234, v234, v94
	v_add_f32_e32 v235, v235, v95
	v_cvt_pk_bf16_f32 v88, v88, v89
	v_cvt_pk_bf16_f32 v89, v90, v91
	v_cvt_pk_bf16_f32 v90, v92, v93
	v_cvt_pk_bf16_f32 v91, v94, v95
	s_nop 1
	s_waitcnt lgkmcnt(2)
	v_mfma_f32_32x32x16_bf16 v[16:31], v[202:205], v[88:91], v[16:31]
	s_waitcnt lgkmcnt(0)
	v_mfma_f32_32x32x16_bf16 v[0:15], v[206:209], v[88:91], v[0:15]
	v_add_f32_e32 v234, v234, v235
	v_add_f32_e32 v176, v176, v234
	v_cmp_lt_f32_e32 vcc, 0x43000000, v234
	s_cbranch_vccz .Lm0_nr_m1A
	s_nop 15
	v_mov_b32_e32 v235, v234
	s_nop 1
	v_permlane32_swap_b32_e32 v234, v235
	v_add_f32_e32 v178, v234, v235
	v_cmp_lt_f32_e32 vcc, 0x43800000, v178
	v_frexp_exp_i32_f32_e32 v179, v178
	s_nop 1
	v_cndmask_b32_e32 v179, 0, v179, vcc
	v_cvt_f32_i32_e32 v180, v179
	v_sub_u32_e32 v179, 0, v179
	v_ldexp_f32 v178, 1.0, v179
	v_add_f32_e32 v168, v168, v180
	v_mul_f32_e32 v176, v176, v178
	v_mul_f32_e32 v0, v0, v178
	v_mul_f32_e32 v1, v1, v178
	v_mul_f32_e32 v2, v2, v178
	v_mul_f32_e32 v3, v3, v178
	v_mul_f32_e32 v4, v4, v178
	v_mul_f32_e32 v5, v5, v178
	v_mul_f32_e32 v6, v6, v178
	v_mul_f32_e32 v7, v7, v178
	v_mul_f32_e32 v8, v8, v178
	v_mul_f32_e32 v9, v9, v178
	v_mul_f32_e32 v10, v10, v178
	v_mul_f32_e32 v11, v11, v178
	v_mul_f32_e32 v12, v12, v178
	v_mul_f32_e32 v13, v13, v178
	v_mul_f32_e32 v14, v14, v178
	v_mul_f32_e32 v15, v15, v178
	v_mul_f32_e32 v16, v16, v178
	v_mul_f32_e32 v17, v17, v178
	v_mul_f32_e32 v18, v18, v178
	v_mul_f32_e32 v19, v19, v178
	v_mul_f32_e32 v20, v20, v178
	v_mul_f32_e32 v21, v21, v178
	v_mul_f32_e32 v22, v22, v178
	v_mul_f32_e32 v23, v23, v178
	v_mul_f32_e32 v24, v24, v178
	v_mul_f32_e32 v25, v25, v178
	v_mul_f32_e32 v26, v26, v178
	v_mul_f32_e32 v27, v27, v178
	v_mul_f32_e32 v28, v28, v178
	v_mul_f32_e32 v29, v29, v178
	v_mul_f32_e32 v30, v30, v178
	v_mul_f32_e32 v31, v31, v178
	v_mul_f32_e32 v218, 0xc0b17218, v168
	v_mov_b32_e32 v219, v218
	v_mov_b32_e32 v220, v218
	v_mov_b32_e32 v221, v218
	v_mov_b32_e32 v222, v218
	v_mov_b32_e32 v223, v218
	v_mov_b32_e32 v224, v218
	v_mov_b32_e32 v225, v218
	v_mov_b32_e32 v226, v218
	v_mov_b32_e32 v227, v218
	v_mov_b32_e32 v228, v218
	v_mov_b32_e32 v229, v218
	v_mov_b32_e32 v230, v218
	v_mov_b32_e32 v231, v218
	v_mov_b32_e32 v232, v218
	v_mov_b32_e32 v233, v218

.Lm0_ctxA:
	v_add_u32_e32 v236, v173, v162
	ds_read_b128 v[128:131], v236
	ds_read_b128 v[144:147], v236 offset:6656
	ds_read_b128 v[132:135], v236 offset:32
	ds_read_b128 v[148:151], v236 offset:6688
	ds_read_b128 v[136:139], v236 offset:64
	ds_read_b128 v[152:155], v236 offset:6720
	ds_read_b128 v[140:143], v236 offset:96
	ds_read_b128 v[156:159], v236 offset:6752
	v_add_u32_e32 v237, v175, v174
	s_waitcnt lgkmcnt(7)
	v_mfma_f32_32x32x16_bf16 v[32:47], v[128:131], v[96:99], v[218:233]
	s_waitcnt lgkmcnt(6)
	v_mfma_f32_32x32x16_bf16 v[48:63], v[144:147], v[96:99], v[218:233]
	s_waitcnt lgkmcnt(5)
	v_mfma_f32_32x32x16_bf16 v[32:47], v[132:135], v[100:103], v[32:47]
	s_waitcnt lgkmcnt(4)
	v_mfma_f32_32x32x16_bf16 v[48:63], v[148:151], v[100:103], v[48:63]
	s_waitcnt lgkmcnt(3)
	v_mfma_f32_32x32x16_bf16 v[32:47], v[136:139], v[104:107], v[32:47]
	s_waitcnt lgkmcnt(2)
	v_mfma_f32_32x32x16_bf16 v[48:63], v[152:155], v[104:107], v[48:63]
	s_waitcnt lgkmcnt(1)
	v_mfma_f32_32x32x16_bf16 v[32:47], v[140:143], v[108:111], v[32:47]
	s_waitcnt lgkmcnt(0)
	v_mfma_f32_32x32x16_bf16 v[48:63], v[156:159], v[108:111], v[48:63]
	ds_read_b64_tr_b16 v[186:187], v237 offset:26624
	ds_read_b64_tr_b16 v[188:189], v237 offset:28160
	ds_read_b64_tr_b16 v[190:191], v237 offset:26688
	ds_read_b64_tr_b16 v[192:193], v237 offset:28224
	ds_read_b64_tr_b16 v[194:195], v237 offset:29696
	ds_read_b64_tr_b16 v[196:197], v237 offset:31232
	ds_read_b64_tr_b16 v[198:199], v237 offset:29760
	ds_read_b64_tr_b16 v[200:201], v237 offset:31296
	ds_read_b64_tr_b16 v[202:203], v237 offset:32768
	ds_read_b64_tr_b16 v[204:205], v237 offset:34304
	ds_read_b64_tr_b16 v[206:207], v237 offset:32832
	ds_read_b64_tr_b16 v[208:209], v237 offset:34368
	ds_read_b64_tr_b16 v[210:211], v237 offset:35840
	ds_read_b64_tr_b16 v[212:213], v237 offset:37376
	ds_read_b64_tr_b16 v[214:215], v237 offset:35904
	ds_read_b64_tr_b16 v[216:217], v237 offset:37440
	v_mul_f32_e32 v32, 0x3e38aa3b, v32
	v_mul_f32_e32 v33, 0x3e38aa3b, v33
	v_mul_f32_e32 v34, 0x3e38aa3b, v34
	v_mul_f32_e32 v35, 0x3e38aa3b, v35
	v_mul_f32_e32 v36, 0x3e38aa3b, v36
	v_mul_f32_e32 v37, 0x3e38aa3b, v37
	v_mul_f32_e32 v38, 0x3e38aa3b, v38
	v_mul_f32_e32 v39, 0x3e38aa3b, v39
	v_exp_f32_e32 v32, v32
	v_exp_f32_e32 v33, v33
	v_exp_f32_e32 v34, v34
	v_exp_f32_e32 v35, v35
	v_exp_f32_e32 v36, v36
	v_exp_f32_e32 v37, v37
	v_exp_f32_e32 v38, v38
	v_exp_f32_e32 v39, v39
	v_add_f32_e32 v234, v32, v34
	v_add_f32_e32 v235, v33, v35
	v_add_f32_e32 v234, v234, v36
	v_add_f32_e32 v235, v235, v37
	v_add_f32_e32 v234, v234, v38
	v_add_f32_e32 v235, v235, v39
	v_cvt_pk_bf16_f32 v32, v32, v33
	v_cvt_pk_bf16_f32 v33, v34, v35
	v_cvt_pk_bf16_f32 v34, v36, v37
	v_cvt_pk_bf16_f32 v35, v38, v39
	v_mul_f32_e32 v40, 0x3e38aa3b, v40
	v_mul_f32_e32 v41, 0x3e38aa3b, v41
	s_waitcnt lgkmcnt(14)
	v_mfma_f32_32x32x16_bf16 v[16:31], v[186:189], v[32:35], v[16:31]
	v_mul_f32_e32 v42, 0x3e38aa3b, v42
	v_mul_f32_e32 v43, 0x3e38aa3b, v43
	v_mul_f32_e32 v44, 0x3e38aa3b, v44
	v_mul_f32_e32 v45, 0x3e38aa3b, v45
	v_mul_f32_e32 v46, 0x3e38aa3b, v46
	v_mul_f32_e32 v47, 0x3e38aa3b, v47
	s_waitcnt lgkmcnt(12)
	v_mfma_f32_32x32x16_bf16 v[0:15], v[190:193], v[32:35], v[0:15]
	v_exp_f32_e32 v40, v40
	v_exp_f32_e32 v41, v41
	v_exp_f32_e32 v42, v42
	v_exp_f32_e32 v43, v43
	v_exp_f32_e32 v44, v44
	v_exp_f32_e32 v45, v45
	v_exp_f32_e32 v46, v46
	v_exp_f32_e32 v47, v47
	v_add_f32_e32 v234, v234, v40
	v_add_f32_e32 v235, v235, v41
	v_add_f32_e32 v234, v234, v42
	v_add_f32_e32 v235, v235, v43
	v_add_f32_e32 v234, v234, v44
	v_add_f32_e32 v235, v235, v45
	v_add_f32_e32 v234, v234, v46
	v_add_f32_e32 v235, v235, v47
	v_cvt_pk_bf16_f32 v40, v40, v41
	v_cvt_pk_bf16_f32 v41, v42, v43
	v_cvt_pk_bf16_f32 v42, v44, v45
	v_cvt_pk_bf16_f32 v43, v46, v47
	v_mul_f32_e32 v48, 0x3e38aa3b, v48
	v_mul_f32_e32 v49, 0x3e38aa3b, v49
	s_waitcnt lgkmcnt(10)
	v_mfma_f32_32x32x16_bf16 v[16:31], v[194:197], v[40:43], v[16:31]
	v_mul_f32_e32 v50, 0x3e38aa3b, v50
	v_mul_f32_e32 v51, 0x3e38aa3b, v51
	v_mul_f32_e32 v52, 0x3e38aa3b, v52
	v_mul_f32_e32 v53, 0x3e38aa3b, v53
	v_mul_f32_e32 v54, 0x3e38aa3b, v54
	v_mul_f32_e32 v55, 0x3e38aa3b, v55
	s_waitcnt lgkmcnt(8)
	v_mfma_f32_32x32x16_bf16 v[0:15], v[198:201], v[40:43], v[0:15]
	v_exp_f32_e32 v48, v48
	v_exp_f32_e32 v49, v49
	v_exp_f32_e32 v50, v50
	v_exp_f32_e32 v51, v51
	v_exp_f32_e32 v52, v52
	v_exp_f32_e32 v53, v53
	v_exp_f32_e32 v54, v54
	v_exp_f32_e32 v55, v55
	v_add_f32_e32 v234, v234, v48
	v_add_f32_e32 v235, v235, v49
	v_add_f32_e32 v234, v234, v50
	v_add_f32_e32 v235, v235, v51
	v_add_f32_e32 v234, v234, v52
	v_add_f32_e32 v235, v235, v53
	v_add_f32_e32 v234, v234, v54
	v_add_f32_e32 v235, v235, v55
	v_cvt_pk_bf16_f32 v48, v48, v49
	v_cvt_pk_bf16_f32 v49, v50, v51
	v_cvt_pk_bf16_f32 v50, v52, v53
	v_cvt_pk_bf16_f32 v51, v54, v55
	v_mul_f32_e32 v56, 0x3e38aa3b, v56
	v_mul_f32_e32 v57, 0x3e38aa3b, v57
	s_waitcnt lgkmcnt(6)
	v_mfma_f32_32x32x16_bf16 v[16:31], v[202:205], v[48:51], v[16:31]
	v_mul_f32_e32 v58, 0x3e38aa3b, v58
	v_mul_f32_e32 v59, 0x3e38aa3b, v59
	v_mul_f32_e32 v60, 0x3e38aa3b, v60
	v_mul_f32_e32 v61, 0x3e38aa3b, v61
	v_mul_f32_e32 v62, 0x3e38aa3b, v62
	v_mul_f32_e32 v63, 0x3e38aa3b, v63
	s_waitcnt lgkmcnt(4)
	v_mfma_f32_32x32x16_bf16 v[0:15], v[206:209], v[48:51], v[0:15]
	v_exp_f32_e32 v56, v56
	v_exp_f32_e32 v57, v57
	v_exp_f32_e32 v58, v58
	v_exp_f32_e32 v59, v59
	v_exp_f32_e32 v60, v60
	v_exp_f32_e32 v61, v61
	v_exp_f32_e32 v62, v62
	v_exp_f32_e32 v63, v63
	v_add_f32_e32 v234, v234, v56
	v_add_f32_e32 v235, v235, v57
	v_add_f32_e32 v234, v234, v58
	v_add_f32_e32 v235, v235, v59
	v_add_f32_e32 v234, v234, v60
	v_add_f32_e32 v235, v235, v61
	v_add_f32_e32 v234, v234, v62
	v_add_f32_e32 v235, v235, v63
	v_cvt_pk_bf16_f32 v56, v56, v57
	v_cvt_pk_bf16_f32 v57, v58, v59
	v_cvt_pk_bf16_f32 v58, v60, v61
	v_cvt_pk_bf16_f32 v59, v62, v63
	s_nop 1
	s_waitcnt lgkmcnt(2)
	v_mfma_f32_32x32x16_bf16 v[16:31], v[210:213], v[56:59], v[16:31]
	s_waitcnt lgkmcnt(0)
	v_mfma_f32_32x32x16_bf16 v[0:15], v[214:217], v[56:59], v[0:15]
	v_add_f32_e32 v234, v234, v235
	v_add_f32_e32 v176, v176, v234
	v_cmp_lt_f32_e32 vcc, 0x43000000, v234
	s_cbranch_vccz .Lm0_nr_cA
	s_nop 15
	v_mov_b32_e32 v235, v234
	s_nop 1
	v_permlane32_swap_b32_e32 v234, v235
	v_add_f32_e32 v178, v234, v235
	v_cmp_lt_f32_e32 vcc, 0x43800000, v178
	v_frexp_exp_i32_f32_e32 v179, v178
	s_nop 1
	v_cndmask_b32_e32 v179, 0, v179, vcc
	v_cvt_f32_i32_e32 v180, v179
	v_sub_u32_e32 v179, 0, v179
	v_ldexp_f32 v178, 1.0, v179
	v_add_f32_e32 v168, v168, v180
	v_mul_f32_e32 v176, v176, v178
	v_mul_f32_e32 v0, v0, v178
	v_mul_f32_e32 v1, v1, v178
	v_mul_f32_e32 v2, v2, v178
	v_mul_f32_e32 v3, v3, v178
	v_mul_f32_e32 v4, v4, v178
	v_mul_f32_e32 v5, v5, v178
	v_mul_f32_e32 v6, v6, v178
	v_mul_f32_e32 v7, v7, v178
	v_mul_f32_e32 v8, v8, v178
	v_mul_f32_e32 v9, v9, v178
	v_mul_f32_e32 v10, v10, v178
	v_mul_f32_e32 v11, v11, v178
	v_mul_f32_e32 v12, v12, v178
	v_mul_f32_e32 v13, v13, v178
	v_mul_f32_e32 v14, v14, v178
	v_mul_f32_e32 v15, v15, v178
	v_mul_f32_e32 v16, v16, v178
	v_mul_f32_e32 v17, v17, v178
	v_mul_f32_e32 v18, v18, v178
	v_mul_f32_e32 v19, v19, v178
	v_mul_f32_e32 v20, v20, v178
	v_mul_f32_e32 v21, v21, v178
	v_mul_f32_e32 v22, v22, v178
	v_mul_f32_e32 v23, v23, v178
	v_mul_f32_e32 v24, v24, v178
	v_mul_f32_e32 v25, v25, v178
	v_mul_f32_e32 v26, v26, v178
	v_mul_f32_e32 v27, v27, v178
	v_mul_f32_e32 v28, v28, v178
	v_mul_f32_e32 v29, v29, v178
	v_mul_f32_e32 v30, v30, v178
	v_mul_f32_e32 v31, v31, v178
	v_mul_f32_e32 v218, 0xc0b17218, v168
	v_mov_b32_e32 v219, v218
	v_mov_b32_e32 v220, v218
	v_mov_b32_e32 v221, v218
	v_mov_b32_e32 v222, v218
	v_mov_b32_e32 v223, v218
	v_mov_b32_e32 v224, v218
	v_mov_b32_e32 v225, v218
	v_mov_b32_e32 v226, v218
	v_mov_b32_e32 v227, v218
	v_mov_b32_e32 v228, v218
	v_mov_b32_e32 v229, v218
	v_mov_b32_e32 v230, v218
	v_mov_b32_e32 v231, v218
	v_mov_b32_e32 v232, v218
	v_mov_b32_e32 v233, v218
.Lm0_nr_cA:
.Lm0_doneA:
	s_add_i32 s24, s47, 1
	s_cmp_ge_i32 s24, s38
	s_cbranch_scc1 .Lm0_nwA
	s_waitcnt vmcnt(3)
	ds_write_b128 v171, v[112:115] offset:13312
	s_waitcnt vmcnt(2)
	ds_write_b128 v172, v[116:119] offset:38912
.Lm0_nwA:
	s_waitcnt lgkmcnt(0)
	s_barrier
	s_add_i32 s24, s47, 3
	s_min_i32 s24, s24, s34
	s_cmp_lt_i32 s24, s35
	s_cselect_b32 s25, s21, s46
	s_cselect_b32 s26, s29, s44
	s_add_i32 s25, s25, s24
	s_lshl_b32 s25, s25, 6
	s_add_i32 s26, s26, s25
	v_add_u32_e32 v236, s26, v161
	v_mad_i64_i32 v[236:237], s[98:99], v236, s33, v[164:165]
	global_load_dwordx4 v[112:115], v[236:237], off
	v_add_u32_e32 v236, s26, v163
	v_mad_i64_i32 v[236:237], s[98:99], v236, s33, v[166:167]
	global_load_dwordx4 v[116:119], v[236:237], off
	s_add_i32 s24, s47, 1
	s_cmp_ge_i32 s24, s38
	s_cbranch_scc1 .Lm0_doneB
	s_cmp_ge_i32 s24, s35
	s_cbranch_scc1 .Lm0_ctxB
	s_add_i32 s25, s20, s24
	s_add_i32 s25, s25, -4
	s_cmp_lt_u32 s25, s39
	s_cbranch_scc1 .Lm0_doneB
	s_cmp_ge_u32 s25, s45
	s_cbranch_scc1 .Lm0_doneB
	s_cmp_lg_u32 s51, 0
	s_cbranch_scc1 .Lm0_m1B
	v_add_u32_e32 v236, v173, v162
	ds_read_b128 v[128:131], v236 offset:13312
	ds_read_b128 v[144:147], v236 offset:19968
	ds_read_b128 v[132:135], v236 offset:13344
	ds_read_b128 v[148:151], v236 offset:20000
	ds_read_b128 v[136:139], v236 offset:13376
	ds_read_b128 v[152:155], v236 offset:20032
	ds_read_b128 v[140:143], v236 offset:13408
	ds_read_b128 v[156:159], v236 offset:20064
	v_add_u32_e32 v237, v175, v174
	s_waitcnt lgkmcnt(7)
	v_mfma_f32_32x32x16_bf16 v[32:47], v[128:131], v[96:99], v[218:233]
	s_waitcnt lgkmcnt(6)
	v_mfma_f32_32x32x16_bf16 v[48:63], v[144:147], v[96:99], v[218:233]
	s_waitcnt lgkmcnt(5)
	v_mfma_f32_32x32x16_bf16 v[32:47], v[132:135], v[100:103], v[32:47]
	s_waitcnt lgkmcnt(4)
	v_mfma_f32_32x32x16_bf16 v[48:63], v[148:151], v[100:103], v[48:63]
	s_waitcnt lgkmcnt(3)
	v_mfma_f32_32x32x16_bf16 v[32:47], v[136:139], v[104:107], v[32:47]
	s_waitcnt lgkmcnt(2)
	v_mfma_f32_32x32x16_bf16 v[48:63], v[152:155], v[104:107], v[48:63]
	s_waitcnt lgkmcnt(1)
	v_mfma_f32_32x32x16_bf16 v[32:47], v[140:143], v[108:111], v[32:47]
	s_waitcnt lgkmcnt(0)
	v_mfma_f32_32x32x16_bf16 v[48:63], v[156:159], v[108:111], v[48:63]
	ds_read_b32 v64, v177 offset:124
	ds_read_b32 v65, v177 offset:128
	ds_read_b32 v66, v177 offset:132
	ds_read_b32 v67, v177 offset:136
	ds_read_b32 v68, v177 offset:156
	ds_read_b32 v69, v177 offset:160
	ds_read_b32 v70, v177 offset:164
	ds_read_b32 v71, v177 offset:168
	ds_read_b32 v72, v177 offset:188
	ds_read_b32 v73, v177 offset:192
	ds_read_b32 v74, v177 offset:196
	ds_read_b32 v75, v177 offset:200
	ds_read_b32 v76, v177 offset:220
	ds_read_b32 v77, v177 offset:224
	ds_read_b32 v78, v177 offset:228
	ds_read_b32 v79, v177 offset:232
	ds_read_b32 v80, v177 offset:252
	ds_read_b32 v81, v177 offset:256
	ds_read_b32 v82, v177 offset:260
	ds_read_b32 v83, v177 offset:264
	ds_read_b32 v84, v177 offset:284
	ds_read_b32 v85, v177 offset:288
	ds_read_b32 v86, v177 offset:292
	ds_read_b32 v87, v177 offset:296
	ds_read_b64_tr_b16 v[186:187], v237 offset:38912
	ds_read_b64_tr_b16 v[188:189], v237 offset:40448
	ds_read_b64_tr_b16 v[190:191], v237 offset:38976
	ds_read_b64_tr_b16 v[192:193], v237 offset:40512
	ds_read_b64_tr_b16 v[194:195], v237 offset:41984
	ds_read_b64_tr_b16 v[196:197], v237 offset:43520
	ds_read_b64_tr_b16 v[198:199], v237 offset:42048
	ds_read_b64_tr_b16 v[200:201], v237 offset:43584
	ds_read_b64_tr_b16 v[202:203], v237 offset:45056
	ds_read_b64_tr_b16 v[204:205], v237 offset:46592
	ds_read_b64_tr_b16 v[206:207], v237 offset:45120
	ds_read_b64_tr_b16 v[208:209], v237 offset:46656
	v_readlane_b32 s24, v255, 33
	v_readlane_b32 s25, v255, 34
	v_readlane_b32 s26, v255, 37
	v_readlane_b32 s27, v255, 38
	s_waitcnt lgkmcnt(12)
	v_fmac_f32_e32 v64, 0x3e38aa3b, v32
	v_fmac_f32_e32 v65, 0x3e38aa3b, v33
	v_fmac_f32_e32 v66, 0x3e38aa3b, v34
	v_fmac_f32_e32 v67, 0x3e38aa3b, v35
	v_fmac_f32_e32 v68, 0x3e38aa3b, v36
	v_fmac_f32_e32 v69, 0x3e38aa3b, v37
	v_fmac_f32_e32 v70, 0x3e38aa3b, v38
	v_fmac_f32_e32 v71, 0x3e38aa3b, v39
	v_cndmask_b32_e64 v64, v64, v238, s[40:41]
	v_cndmask_b32_e64 v65, v65, v238, s[24:25]
	v_cndmask_b32_e64 v66, v66, v238, s[26:27]
	v_cndmask_b32_e64 v67, v67, v238, s[56:57]
	v_cndmask_b32_e64 v68, v68, v238, s[62:63]
	v_cndmask_b32_e64 v69, v69, v238, s[68:69]
	v_cndmask_b32_e64 v70, v70, v238, s[74:75]
	v_cndmask_b32_e64 v71, v71, v238, s[80:81]
	v_exp_f32_e32 v64, v64
	v_exp_f32_e32 v65, v65
	v_exp_f32_e32 v66, v66
	v_exp_f32_e32 v67, v67
	v_exp_f32_e32 v68, v68
	v_exp_f32_e32 v69, v69
	v_exp_f32_e32 v70, v70
	v_exp_f32_e32 v71, v71
	v_add_f32_e32 v234, v64, v66
	v_add_f32_e32 v235, v65, v67
	v_add_f32_e32 v234, v234, v68
	v_add_f32_e32 v235, v235, v69
	v_add_f32_e32 v234, v234, v70
	v_add_f32_e32 v235, v235, v71
	v_cvt_pk_bf16_f32 v64, v64, v65
	v_cvt_pk_bf16_f32 v65, v66, v67
	v_cvt_pk_bf16_f32 v66, v68, v69
	v_cvt_pk_bf16_f32 v67, v70, v71
	v_fmac_f32_e32 v72, 0x3e38aa3b, v40
	v_fmac_f32_e32 v73, 0x3e38aa3b, v41
	s_waitcnt lgkmcnt(10)
	v_mfma_f32_32x32x16_bf16 v[16:31], v[186:189], v[64:67], v[16:31]
	v_fmac_f32_e32 v74, 0x3e38aa3b, v42
	v_fmac_f32_e32 v75, 0x3e38aa3b, v43
	v_fmac_f32_e32 v76, 0x3e38aa3b, v44
	v_fmac_f32_e32 v77, 0x3e38aa3b, v45
	v_fmac_f32_e32 v78, 0x3e38aa3b, v46
	v_fmac_f32_e32 v79, 0x3e38aa3b, v47
	s_waitcnt lgkmcnt(8)
	v_mfma_f32_32x32x16_bf16 v[0:15], v[190:193], v[64:67], v[0:15]
	v_cndmask_b32_e64 v72, v238, v72, s[86:87]
	v_cndmask_b32_e64 v73, v238, v73, s[90:91]
	v_cndmask_b32_e64 v74, v238, v74, s[94:95]
	v_cndmask_b32_e64 v75, v238, v75, s[0:1]
	v_cndmask_b32_e64 v76, v238, v76, s[4:5]
	v_cndmask_b32_e64 v77, v238, v77, s[8:9]
	v_cndmask_b32_e64 v78, v238, v78, s[12:13]
	v_cndmask_b32_e64 v79, v238, v79, s[16:17]
	v_exp_f32_e32 v72, v72
	v_exp_f32_e32 v73, v73
	v_exp_f32_e32 v74, v74
	v_exp_f32_e32 v75, v75
	v_exp_f32_e32 v76, v76
	v_exp_f32_e32 v77, v77
	v_exp_f32_e32 v78, v78
	v_exp_f32_e32 v79, v79
	v_add_f32_e32 v234, v234, v72
	v_add_f32_e32 v235, v235, v73
	v_add_f32_e32 v234, v234, v74
	v_add_f32_e32 v235, v235, v75
	v_add_f32_e32 v234, v234, v76
	v_add_f32_e32 v235, v235, v77
	v_add_f32_e32 v234, v234, v78
	v_add_f32_e32 v235, v235, v79
	v_cvt_pk_bf16_f32 v72, v72, v73
	v_cvt_pk_bf16_f32 v73, v74, v75
	v_cvt_pk_bf16_f32 v74, v76, v77
	v_cvt_pk_bf16_f32 v75, v78, v79
	v_fmac_f32_e32 v80, 0x3e38aa3b, v48
	v_fmac_f32_e32 v81, 0x3e38aa3b, v49
	s_waitcnt lgkmcnt(6)
	v_mfma_f32_32x32x16_bf16 v[16:31], v[194:197], v[72:75], v[16:31]
	v_fmac_f32_e32 v82, 0x3e38aa3b, v50
	v_fmac_f32_e32 v83, 0x3e38aa3b, v51
	v_fmac_f32_e32 v84, 0x3e38aa3b, v52
	v_fmac_f32_e32 v85, 0x3e38aa3b, v53
	v_fmac_f32_e32 v86, 0x3e38aa3b, v54
	v_fmac_f32_e32 v87, 0x3e38aa3b, v55
	s_waitcnt lgkmcnt(4)
	v_mfma_f32_32x32x16_bf16 v[0:15], v[198:201], v[72:75], v[0:15]
	v_cndmask_b32_e64 v80, v238, v80, s[42:43]
	v_cndmask_b32_e64 v81, v238, v81, s[48:49]
	v_cndmask_b32_e64 v82, v238, v82, s[54:55]
	v_cndmask_b32_e64 v83, v238, v83, s[60:61]
	v_cndmask_b32_e64 v84, v238, v84, s[66:67]
	v_cndmask_b32_e64 v85, v238, v85, s[72:73]
	v_cndmask_b32_e64 v86, v238, v86, s[78:79]
	v_cndmask_b32_e64 v87, v238, v87, s[84:85]
	v_exp_f32_e32 v80, v80
	v_exp_f32_e32 v81, v81
	v_exp_f32_e32 v82, v82
	v_exp_f32_e32 v83, v83
	v_exp_f32_e32 v84, v84
	v_exp_f32_e32 v85, v85
	v_exp_f32_e32 v86, v86
	v_exp_f32_e32 v87, v87
	v_add_f32_e32 v234, v234, v80
	v_add_f32_e32 v235, v235, v81
	v_add_f32_e32 v234, v234, v82
	v_add_f32_e32 v235, v235, v83
	v_add_f32_e32 v234, v234, v84
	v_add_f32_e32 v235, v235, v85
	v_add_f32_e32 v234, v234, v86
	v_add_f32_e32 v235, v235, v87
	v_cvt_pk_bf16_f32 v80, v80, v81
	v_cvt_pk_bf16_f32 v81, v82, v83
	v_cvt_pk_bf16_f32 v82, v84, v85
	v_cvt_pk_bf16_f32 v83, v86, v87
	s_nop 1
	s_waitcnt lgkmcnt(2)
	v_mfma_f32_32x32x16_bf16 v[16:31], v[202:205], v[80:83], v[16:31]
	s_waitcnt lgkmcnt(0)
	v_mfma_f32_32x32x16_bf16 v[0:15], v[206:209], v[80:83], v[0:15]
	v_add_f32_e32 v234, v234, v235
	v_add_f32_e32 v176, v176, v234
	v_cmp_lt_f32_e32 vcc, 0x43000000, v234
	s_cbranch_vccz .Lm0_nr_m0B
	s_nop 15
	v_mov_b32_e32 v235, v234
	s_nop 1
	v_permlane32_swap_b32_e32 v234, v235
	v_add_f32_e32 v178, v234, v235
	v_cmp_lt_f32_e32 vcc, 0x43800000, v178
	v_frexp_exp_i32_f32_e32 v179, v178
	s_nop 1
	v_cndmask_b32_e32 v179, 0, v179, vcc
	v_cvt_f32_i32_e32 v180, v179
	v_sub_u32_e32 v179, 0, v179
	v_ldexp_f32 v178, 1.0, v179
	v_add_f32_e32 v168, v168, v180
	v_mul_f32_e32 v176, v176, v178
	v_mul_f32_e32 v0, v0, v178
	v_mul_f32_e32 v1, v1, v178
	v_mul_f32_e32 v2, v2, v178
	v_mul_f32_e32 v3, v3, v178
	v_mul_f32_e32 v4, v4, v178
	v_mul_f32_e32 v5, v5, v178
	v_mul_f32_e32 v6, v6, v178
	v_mul_f32_e32 v7, v7, v178
	v_mul_f32_e32 v8, v8, v178
	v_mul_f32_e32 v9, v9, v178
	v_mul_f32_e32 v10, v10, v178
	v_mul_f32_e32 v11, v11, v178
	v_mul_f32_e32 v12, v12, v178
	v_mul_f32_e32 v13, v13, v178
	v_mul_f32_e32 v14, v14, v178
	v_mul_f32_e32 v15, v15, v178
	v_mul_f32_e32 v16, v16, v178
	v_mul_f32_e32 v17, v17, v178
	v_mul_f32_e32 v18, v18, v178
	v_mul_f32_e32 v19, v19, v178
	v_mul_f32_e32 v20, v20, v178
	v_mul_f32_e32 v21, v21, v178
	v_mul_f32_e32 v22, v22, v178
	v_mul_f32_e32 v23, v23, v178
	v_mul_f32_e32 v24, v24, v178
	v_mul_f32_e32 v25, v25, v178
	v_mul_f32_e32 v26, v26, v178
	v_mul_f32_e32 v27, v27, v178
	v_mul_f32_e32 v28, v28, v178
	v_mul_f32_e32 v29, v29, v178
	v_mul_f32_e32 v30, v30, v178
	v_mul_f32_e32 v31, v31, v178
	v_mul_f32_e32 v218, 0xc0b17218, v168
	v_mov_b32_e32 v219, v218
	v_mov_b32_e32 v220, v218
	v_mov_b32_e32 v221, v218
	v_mov_b32_e32 v222, v218
	v_mov_b32_e32 v223, v218
	v_mov_b32_e32 v224, v218
	v_mov_b32_e32 v225, v218
	v_mov_b32_e32 v226, v218
	v_mov_b32_e32 v227, v218
	v_mov_b32_e32 v228, v218
	v_mov_b32_e32 v229, v218
	v_mov_b32_e32 v230, v218
	v_mov_b32_e32 v231, v218
	v_mov_b32_e32 v232, v218
	v_mov_b32_e32 v233, v218

.Lm0_m1B:
	v_add_u32_e32 v236, v173, v162
	ds_read_b128 v[128:131], v236 offset:13312
	ds_read_b128 v[144:147], v236 offset:19968
	ds_read_b128 v[132:135], v236 offset:13344
	ds_read_b128 v[148:151], v236 offset:20000
	ds_read_b128 v[136:139], v236 offset:13376
	ds_read_b128 v[152:155], v236 offset:20032
	ds_read_b128 v[140:143], v236 offset:13408
	ds_read_b128 v[156:159], v236 offset:20064
	v_add_u32_e32 v237, v175, v174
	s_waitcnt lgkmcnt(7)
	v_mfma_f32_32x32x16_bf16 v[32:47], v[128:131], v[96:99], v[218:233]
	s_waitcnt lgkmcnt(6)
	v_mfma_f32_32x32x16_bf16 v[48:63], v[144:147], v[96:99], v[218:233]
	s_waitcnt lgkmcnt(5)
	v_mfma_f32_32x32x16_bf16 v[32:47], v[132:135], v[100:103], v[32:47]
	s_waitcnt lgkmcnt(4)
	v_mfma_f32_32x32x16_bf16 v[48:63], v[148:151], v[100:103], v[48:63]
	s_waitcnt lgkmcnt(3)
	v_mfma_f32_32x32x16_bf16 v[32:47], v[136:139], v[104:107], v[32:47]
	s_waitcnt lgkmcnt(2)
	v_mfma_f32_32x32x16_bf16 v[48:63], v[152:155], v[104:107], v[48:63]
	s_waitcnt lgkmcnt(1)
	v_mfma_f32_32x32x16_bf16 v[32:47], v[140:143], v[108:111], v[32:47]
	s_waitcnt lgkmcnt(0)
	v_mfma_f32_32x32x16_bf16 v[48:63], v[156:159], v[108:111], v[48:63]
	ds_read_b32 v72, v177 offset:188
	ds_read_b32 v73, v177 offset:192
	ds_read_b32 v74, v177 offset:196
	ds_read_b32 v75, v177 offset:200
	ds_read_b32 v76, v177 offset:220
	ds_read_b32 v77, v177 offset:224
	ds_read_b32 v78, v177 offset:228
	ds_read_b32 v79, v177 offset:232
	ds_read_b32 v80, v177 offset:252
	ds_read_b32 v81, v177 offset:256
	ds_read_b32 v82, v177 offset:260
	ds_read_b32 v83, v177 offset:264
	ds_read_b32 v84, v177 offset:284
	ds_read_b32 v85, v177 offset:288
	ds_read_b32 v86, v177 offset:292
	ds_read_b32 v87, v177 offset:296
	ds_read_b32 v88, v177 offset:316
	ds_read_b32 v89, v177 offset:320
	ds_read_b32 v90, v177 offset:324
	ds_read_b32 v91, v177 offset:328
	ds_read_b32 v92, v177 offset:348
	ds_read_b32 v93, v177 offset:352
	ds_read_b32 v94, v177 offset:356
	ds_read_b32 v95, v177 offset:360
	ds_read_b64_tr_b16 v[186:187], v237 offset:41984
	ds_read_b64_tr_b16 v[188:189], v237 offset:43520
	ds_read_b64_tr_b16 v[190:191], v237 offset:42048
	ds_read_b64_tr_b16 v[192:193], v237 offset:43584
	ds_read_b64_tr_b16 v[194:195], v237 offset:45056
	ds_read_b64_tr_b16 v[196:197], v237 offset:46592
	ds_read_b64_tr_b16 v[198:199], v237 offset:45120
	ds_read_b64_tr_b16 v[200:201], v237 offset:46656
	ds_read_b64_tr_b16 v[202:203], v237 offset:48128
	ds_read_b64_tr_b16 v[204:205], v237 offset:49664
	ds_read_b64_tr_b16 v[206:207], v237 offset:48192
	ds_read_b64_tr_b16 v[208:209], v237 offset:49728
	s_waitcnt lgkmcnt(12)
	v_fmac_f32_e32 v72, 0x3e38aa3b, v40
	v_fmac_f32_e32 v73, 0x3e38aa3b, v41
	v_fmac_f32_e32 v74, 0x3e38aa3b, v42
	v_fmac_f32_e32 v75, 0x3e38aa3b, v43
	v_fmac_f32_e32 v76, 0x3e38aa3b, v44
	v_fmac_f32_e32 v77, 0x3e38aa3b, v45
	v_fmac_f32_e32 v78, 0x3e38aa3b, v46
	v_fmac_f32_e32 v79, 0x3e38aa3b, v47
	v_cndmask_b32_e64 v72, v238, v72, s[86:87]
	v_cndmask_b32_e64 v73, v238, v73, s[90:91]
	v_cndmask_b32_e64 v74, v238, v74, s[94:95]
	v_cndmask_b32_e64 v75, v238, v75, s[0:1]
	v_cndmask_b32_e64 v76, v238, v76, s[4:5]
	v_cndmask_b32_e64 v77, v238, v77, s[8:9]
	v_cndmask_b32_e64 v78, v238, v78, s[12:13]
	v_cndmask_b32_e64 v79, v238, v79, s[16:17]
	v_exp_f32_e32 v72, v72
	v_exp_f32_e32 v73, v73
	v_exp_f32_e32 v74, v74
	v_exp_f32_e32 v75, v75
	v_exp_f32_e32 v76, v76
	v_exp_f32_e32 v77, v77
	v_exp_f32_e32 v78, v78
	v_exp_f32_e32 v79, v79
	v_add_f32_e32 v234, v72, v74
	v_add_f32_e32 v235, v73, v75
	v_add_f32_e32 v234, v234, v76
	v_add_f32_e32 v235, v235, v77
	v_add_f32_e32 v234, v234, v78
	v_add_f32_e32 v235, v235, v79
	v_cvt_pk_bf16_f32 v72, v72, v73
	v_cvt_pk_bf16_f32 v73, v74, v75
	v_cvt_pk_bf16_f32 v74, v76, v77
	v_cvt_pk_bf16_f32 v75, v78, v79
	v_fmac_f32_e32 v80, 0x3e38aa3b, v48
	v_fmac_f32_e32 v81, 0x3e38aa3b, v49
	s_waitcnt lgkmcnt(10)
	v_mfma_f32_32x32x16_bf16 v[16:31], v[186:189], v[72:75], v[16:31]
	v_fmac_f32_e32 v82, 0x3e38aa3b, v50
	v_fmac_f32_e32 v83, 0x3e38aa3b, v51
	v_fmac_f32_e32 v84, 0x3e38aa3b, v52
	v_fmac_f32_e32 v85, 0x3e38aa3b, v53
	v_fmac_f32_e32 v86, 0x3e38aa3b, v54
	v_fmac_f32_e32 v87, 0x3e38aa3b, v55
	s_waitcnt lgkmcnt(8)
	v_mfma_f32_32x32x16_bf16 v[0:15], v[190:193], v[72:75], v[0:15]
	v_cndmask_b32_e64 v80, v238, v80, s[42:43]
	v_cndmask_b32_e64 v81, v238, v81, s[48:49]
	v_cndmask_b32_e64 v82, v238, v82, s[54:55]
	v_cndmask_b32_e64 v83, v238, v83, s[60:61]
	v_cndmask_b32_e64 v84, v238, v84, s[66:67]
	v_cndmask_b32_e64 v85, v238, v85, s[72:73]
	v_cndmask_b32_e64 v86, v238, v86, s[78:79]
	v_cndmask_b32_e64 v87, v238, v87, s[84:85]
	v_exp_f32_e32 v80, v80
	v_exp_f32_e32 v81, v81
	v_exp_f32_e32 v82, v82
	v_exp_f32_e32 v83, v83
	v_exp_f32_e32 v84, v84
	v_exp_f32_e32 v85, v85
	v_exp_f32_e32 v86, v86
	v_exp_f32_e32 v87, v87
	v_add_f32_e32 v234, v234, v80
	v_add_f32_e32 v235, v235, v81
	v_add_f32_e32 v234, v234, v82
	v_add_f32_e32 v235, v235, v83
	v_add_f32_e32 v234, v234, v84
	v_add_f32_e32 v235, v235, v85
	v_add_f32_e32 v234, v234, v86
	v_add_f32_e32 v235, v235, v87
	v_cvt_pk_bf16_f32 v80, v80, v81
	v_cvt_pk_bf16_f32 v81, v82, v83
	v_cvt_pk_bf16_f32 v82, v84, v85
	v_cvt_pk_bf16_f32 v83, v86, v87
	v_fmac_f32_e32 v88, 0x3e38aa3b, v56
	v_fmac_f32_e32 v89, 0x3e38aa3b, v57
	s_waitcnt lgkmcnt(6)
	v_mfma_f32_32x32x16_bf16 v[16:31], v[194:197], v[80:83], v[16:31]
	v_fmac_f32_e32 v90, 0x3e38aa3b, v58
	v_fmac_f32_e32 v91, 0x3e38aa3b, v59
	v_fmac_f32_e32 v92, 0x3e38aa3b, v60
	v_fmac_f32_e32 v93, 0x3e38aa3b, v61
	v_fmac_f32_e32 v94, 0x3e38aa3b, v62
	v_fmac_f32_e32 v95, 0x3e38aa3b, v63
	s_waitcnt lgkmcnt(4)
	v_mfma_f32_32x32x16_bf16 v[0:15], v[198:201], v[80:83], v[0:15]
	v_cndmask_b32_e64 v88, v238, v88, s[88:89]
	v_cndmask_b32_e64 v89, v238, v89, s[92:93]
	v_cndmask_b32_e64 v90, v238, v90, s[96:97]
	v_cndmask_b32_e64 v91, v238, v91, s[2:3]
	v_cndmask_b32_e64 v92, v238, v92, s[6:7]
	v_cndmask_b32_e64 v93, v238, v93, s[10:11]
	v_cndmask_b32_e64 v94, v238, v94, s[14:15]
	v_cndmask_b32_e64 v95, v238, v95, s[18:19]
	v_exp_f32_e32 v88, v88
	v_exp_f32_e32 v89, v89
	v_exp_f32_e32 v90, v90
	v_exp_f32_e32 v91, v91
	v_exp_f32_e32 v92, v92
	v_exp_f32_e32 v93, v93
	v_exp_f32_e32 v94, v94
	v_exp_f32_e32 v95, v95
	v_add_f32_e32 v234, v234, v88
	v_add_f32_e32 v235, v235, v89
	v_add_f32_e32 v234, v234, v90
	v_add_f32_e32 v235, v235, v91
	v_add_f32_e32 v234, v234, v92
	v_add_f32_e32 v235, v235, v93
	v_add_f32_e32 v234, v234, v94
	v_add_f32_e32 v235, v235, v95
	v_cvt_pk_bf16_f32 v88, v88, v89
	v_cvt_pk_bf16_f32 v89, v90, v91
	v_cvt_pk_bf16_f32 v90, v92, v93
	v_cvt_pk_bf16_f32 v91, v94, v95
	s_nop 1
	s_waitcnt lgkmcnt(2)
	v_mfma_f32_32x32x16_bf16 v[16:31], v[202:205], v[88:91], v[16:31]
	s_waitcnt lgkmcnt(0)
	v_mfma_f32_32x32x16_bf16 v[0:15], v[206:209], v[88:91], v[0:15]
	v_add_f32_e32 v234, v234, v235
	v_add_f32_e32 v176, v176, v234
	v_cmp_lt_f32_e32 vcc, 0x43000000, v234
	s_cbranch_vccz .Lm0_nr_m1B
	s_nop 15
	v_mov_b32_e32 v235, v234
	s_nop 1
	v_permlane32_swap_b32_e32 v234, v235
	v_add_f32_e32 v178, v234, v235
	v_cmp_lt_f32_e32 vcc, 0x43800000, v178
	v_frexp_exp_i32_f32_e32 v179, v178
	s_nop 1
	v_cndmask_b32_e32 v179, 0, v179, vcc
	v_cvt_f32_i32_e32 v180, v179
	v_sub_u32_e32 v179, 0, v179
	v_ldexp_f32 v178, 1.0, v179
	v_add_f32_e32 v168, v168, v180
	v_mul_f32_e32 v176, v176, v178
	v_mul_f32_e32 v0, v0, v178
	v_mul_f32_e32 v1, v1, v178
	v_mul_f32_e32 v2, v2, v178
	v_mul_f32_e32 v3, v3, v178
	v_mul_f32_e32 v4, v4, v178
	v_mul_f32_e32 v5, v5, v178
	v_mul_f32_e32 v6, v6, v178
	v_mul_f32_e32 v7, v7, v178
	v_mul_f32_e32 v8, v8, v178
	v_mul_f32_e32 v9, v9, v178
	v_mul_f32_e32 v10, v10, v178
	v_mul_f32_e32 v11, v11, v178
	v_mul_f32_e32 v12, v12, v178
	v_mul_f32_e32 v13, v13, v178
	v_mul_f32_e32 v14, v14, v178
	v_mul_f32_e32 v15, v15, v178
	v_mul_f32_e32 v16, v16, v178
	v_mul_f32_e32 v17, v17, v178
	v_mul_f32_e32 v18, v18, v178
	v_mul_f32_e32 v19, v19, v178
	v_mul_f32_e32 v20, v20, v178
	v_mul_f32_e32 v21, v21, v178
	v_mul_f32_e32 v22, v22, v178
	v_mul_f32_e32 v23, v23, v178
	v_mul_f32_e32 v24, v24, v178
	v_mul_f32_e32 v25, v25, v178
	v_mul_f32_e32 v26, v26, v178
	v_mul_f32_e32 v27, v27, v178
	v_mul_f32_e32 v28, v28, v178
	v_mul_f32_e32 v29, v29, v178
	v_mul_f32_e32 v30, v30, v178
	v_mul_f32_e32 v31, v31, v178
	v_mul_f32_e32 v218, 0xc0b17218, v168
	v_mov_b32_e32 v219, v218
	v_mov_b32_e32 v220, v218
	v_mov_b32_e32 v221, v218
	v_mov_b32_e32 v222, v218
	v_mov_b32_e32 v223, v218
	v_mov_b32_e32 v224, v218
	v_mov_b32_e32 v225, v218
	v_mov_b32_e32 v226, v218
	v_mov_b32_e32 v227, v218
	v_mov_b32_e32 v228, v218
	v_mov_b32_e32 v229, v218
	v_mov_b32_e32 v230, v218
	v_mov_b32_e32 v231, v218
	v_mov_b32_e32 v232, v218
	v_mov_b32_e32 v233, v218

.Lm0_ctxB:
	v_add_u32_e32 v236, v173, v162
	ds_read_b128 v[128:131], v236 offset:13312
	ds_read_b128 v[144:147], v236 offset:19968
	ds_read_b128 v[132:135], v236 offset:13344
	ds_read_b128 v[148:151], v236 offset:20000
	ds_read_b128 v[136:139], v236 offset:13376
	ds_read_b128 v[152:155], v236 offset:20032
	ds_read_b128 v[140:143], v236 offset:13408
	ds_read_b128 v[156:159], v236 offset:20064
	v_add_u32_e32 v237, v175, v174
	s_waitcnt lgkmcnt(7)
	v_mfma_f32_32x32x16_bf16 v[32:47], v[128:131], v[96:99], v[218:233]
	s_waitcnt lgkmcnt(6)
	v_mfma_f32_32x32x16_bf16 v[48:63], v[144:147], v[96:99], v[218:233]
	s_waitcnt lgkmcnt(5)
	v_mfma_f32_32x32x16_bf16 v[32:47], v[132:135], v[100:103], v[32:47]
	s_waitcnt lgkmcnt(4)
	v_mfma_f32_32x32x16_bf16 v[48:63], v[148:151], v[100:103], v[48:63]
	s_waitcnt lgkmcnt(3)
	v_mfma_f32_32x32x16_bf16 v[32:47], v[136:139], v[104:107], v[32:47]
	s_waitcnt lgkmcnt(2)
	v_mfma_f32_32x32x16_bf16 v[48:63], v[152:155], v[104:107], v[48:63]
	s_waitcnt lgkmcnt(1)
	v_mfma_f32_32x32x16_bf16 v[32:47], v[140:143], v[108:111], v[32:47]
	s_waitcnt lgkmcnt(0)
	v_mfma_f32_32x32x16_bf16 v[48:63], v[156:159], v[108:111], v[48:63]
	ds_read_b64_tr_b16 v[186:187], v237 offset:38912
	ds_read_b64_tr_b16 v[188:189], v237 offset:40448
	ds_read_b64_tr_b16 v[190:191], v237 offset:38976
	ds_read_b64_tr_b16 v[192:193], v237 offset:40512
	ds_read_b64_tr_b16 v[194:195], v237 offset:41984
	ds_read_b64_tr_b16 v[196:197], v237 offset:43520
	ds_read_b64_tr_b16 v[198:199], v237 offset:42048
	ds_read_b64_tr_b16 v[200:201], v237 offset:43584
	ds_read_b64_tr_b16 v[202:203], v237 offset:45056
	ds_read_b64_tr_b16 v[204:205], v237 offset:46592
	ds_read_b64_tr_b16 v[206:207], v237 offset:45120
	ds_read_b64_tr_b16 v[208:209], v237 offset:46656
	ds_read_b64_tr_b16 v[210:211], v237 offset:48128
	ds_read_b64_tr_b16 v[212:213], v237 offset:49664
	ds_read_b64_tr_b16 v[214:215], v237 offset:48192
	ds_read_b64_tr_b16 v[216:217], v237 offset:49728
	v_mul_f32_e32 v32, 0x3e38aa3b, v32
	v_mul_f32_e32 v33, 0x3e38aa3b, v33
	v_mul_f32_e32 v34, 0x3e38aa3b, v34
	v_mul_f32_e32 v35, 0x3e38aa3b, v35
	v_mul_f32_e32 v36, 0x3e38aa3b, v36
	v_mul_f32_e32 v37, 0x3e38aa3b, v37
	v_mul_f32_e32 v38, 0x3e38aa3b, v38
	v_mul_f32_e32 v39, 0x3e38aa3b, v39
	v_exp_f32_e32 v32, v32
	v_exp_f32_e32 v33, v33
	v_exp_f32_e32 v34, v34
	v_exp_f32_e32 v35, v35
	v_exp_f32_e32 v36, v36
	v_exp_f32_e32 v37, v37
	v_exp_f32_e32 v38, v38
	v_exp_f32_e32 v39, v39
	v_add_f32_e32 v234, v32, v34
	v_add_f32_e32 v235, v33, v35
	v_add_f32_e32 v234, v234, v36
	v_add_f32_e32 v235, v235, v37
	v_add_f32_e32 v234, v234, v38
	v_add_f32_e32 v235, v235, v39
	v_cvt_pk_bf16_f32 v32, v32, v33
	v_cvt_pk_bf16_f32 v33, v34, v35
	v_cvt_pk_bf16_f32 v34, v36, v37
	v_cvt_pk_bf16_f32 v35, v38, v39
	v_mul_f32_e32 v40, 0x3e38aa3b, v40
	v_mul_f32_e32 v41, 0x3e38aa3b, v41
	s_waitcnt lgkmcnt(14)
	v_mfma_f32_32x32x16_bf16 v[16:31], v[186:189], v[32:35], v[16:31]
	v_mul_f32_e32 v42, 0x3e38aa3b, v42
	v_mul_f32_e32 v43, 0x3e38aa3b, v43
	v_mul_f32_e32 v44, 0x3e38aa3b, v44
	v_mul_f32_e32 v45, 0x3e38aa3b, v45
	v_mul_f32_e32 v46, 0x3e38aa3b, v46
	v_mul_f32_e32 v47, 0x3e38aa3b, v47
	s_waitcnt lgkmcnt(12)
	v_mfma_f32_32x32x16_bf16 v[0:15], v[190:193], v[32:35], v[0:15]
	v_exp_f32_e32 v40, v40
	v_exp_f32_e32 v41, v41
	v_exp_f32_e32 v42, v42
	v_exp_f32_e32 v43, v43
	v_exp_f32_e32 v44, v44
	v_exp_f32_e32 v45, v45
	v_exp_f32_e32 v46, v46
	v_exp_f32_e32 v47, v47
	v_add_f32_e32 v234, v234, v40
	v_add_f32_e32 v235, v235, v41
	v_add_f32_e32 v234, v234, v42
	v_add_f32_e32 v235, v235, v43
	v_add_f32_e32 v234, v234, v44
	v_add_f32_e32 v235, v235, v45
	v_add_f32_e32 v234, v234, v46
	v_add_f32_e32 v235, v235, v47
	v_cvt_pk_bf16_f32 v40, v40, v41
	v_cvt_pk_bf16_f32 v41, v42, v43
	v_cvt_pk_bf16_f32 v42, v44, v45
	v_cvt_pk_bf16_f32 v43, v46, v47
	v_mul_f32_e32 v48, 0x3e38aa3b, v48
	v_mul_f32_e32 v49, 0x3e38aa3b, v49
	s_waitcnt lgkmcnt(10)
	v_mfma_f32_32x32x16_bf16 v[16:31], v[194:197], v[40:43], v[16:31]
	v_mul_f32_e32 v50, 0x3e38aa3b, v50
	v_mul_f32_e32 v51, 0x3e38aa3b, v51
	v_mul_f32_e32 v52, 0x3e38aa3b, v52
	v_mul_f32_e32 v53, 0x3e38aa3b, v53
	v_mul_f32_e32 v54, 0x3e38aa3b, v54
	v_mul_f32_e32 v55, 0x3e38aa3b, v55
	s_waitcnt lgkmcnt(8)
	v_mfma_f32_32x32x16_bf16 v[0:15], v[198:201], v[40:43], v[0:15]
	v_exp_f32_e32 v48, v48
	v_exp_f32_e32 v49, v49
	v_exp_f32_e32 v50, v50
	v_exp_f32_e32 v51, v51
	v_exp_f32_e32 v52, v52
	v_exp_f32_e32 v53, v53
	v_exp_f32_e32 v54, v54
	v_exp_f32_e32 v55, v55
	v_add_f32_e32 v234, v234, v48
	v_add_f32_e32 v235, v235, v49
	v_add_f32_e32 v234, v234, v50
	v_add_f32_e32 v235, v235, v51
	v_add_f32_e32 v234, v234, v52
	v_add_f32_e32 v235, v235, v53
	v_add_f32_e32 v234, v234, v54
	v_add_f32_e32 v235, v235, v55
	v_cvt_pk_bf16_f32 v48, v48, v49
	v_cvt_pk_bf16_f32 v49, v50, v51
	v_cvt_pk_bf16_f32 v50, v52, v53
	v_cvt_pk_bf16_f32 v51, v54, v55
	v_mul_f32_e32 v56, 0x3e38aa3b, v56
	v_mul_f32_e32 v57, 0x3e38aa3b, v57
	s_waitcnt lgkmcnt(6)
	v_mfma_f32_32x32x16_bf16 v[16:31], v[202:205], v[48:51], v[16:31]
	v_mul_f32_e32 v58, 0x3e38aa3b, v58
	v_mul_f32_e32 v59, 0x3e38aa3b, v59
	v_mul_f32_e32 v60, 0x3e38aa3b, v60
	v_mul_f32_e32 v61, 0x3e38aa3b, v61
	v_mul_f32_e32 v62, 0x3e38aa3b, v62
	v_mul_f32_e32 v63, 0x3e38aa3b, v63
	s_waitcnt lgkmcnt(4)
	v_mfma_f32_32x32x16_bf16 v[0:15], v[206:209], v[48:51], v[0:15]
	v_exp_f32_e32 v56, v56
	v_exp_f32_e32 v57, v57
	v_exp_f32_e32 v58, v58
	v_exp_f32_e32 v59, v59
	v_exp_f32_e32 v60, v60
	v_exp_f32_e32 v61, v61
	v_exp_f32_e32 v62, v62
	v_exp_f32_e32 v63, v63
	v_add_f32_e32 v234, v234, v56
	v_add_f32_e32 v235, v235, v57
	v_add_f32_e32 v234, v234, v58
	v_add_f32_e32 v235, v235, v59
	v_add_f32_e32 v234, v234, v60
	v_add_f32_e32 v235, v235, v61
	v_add_f32_e32 v234, v234, v62
	v_add_f32_e32 v235, v235, v63
	v_cvt_pk_bf16_f32 v56, v56, v57
	v_cvt_pk_bf16_f32 v57, v58, v59
	v_cvt_pk_bf16_f32 v58, v60, v61
	v_cvt_pk_bf16_f32 v59, v62, v63
	s_nop 1
	s_waitcnt lgkmcnt(2)
	v_mfma_f32_32x32x16_bf16 v[16:31], v[210:213], v[56:59], v[16:31]
	s_waitcnt lgkmcnt(0)
	v_mfma_f32_32x32x16_bf16 v[0:15], v[214:217], v[56:59], v[0:15]
	v_add_f32_e32 v234, v234, v235
	v_add_f32_e32 v176, v176, v234
	v_cmp_lt_f32_e32 vcc, 0x43000000, v234
	s_cbranch_vccz .Lm0_nr_cB
	s_nop 15
	v_mov_b32_e32 v235, v234
	s_nop 1
	v_permlane32_swap_b32_e32 v234, v235
	v_add_f32_e32 v178, v234, v235
	v_cmp_lt_f32_e32 vcc, 0x43800000, v178
	v_frexp_exp_i32_f32_e32 v179, v178
	s_nop 1
	v_cndmask_b32_e32 v179, 0, v179, vcc
	v_cvt_f32_i32_e32 v180, v179
	v_sub_u32_e32 v179, 0, v179
	v_ldexp_f32 v178, 1.0, v179
	v_add_f32_e32 v168, v168, v180
	v_mul_f32_e32 v176, v176, v178
	v_mul_f32_e32 v0, v0, v178
	v_mul_f32_e32 v1, v1, v178
	v_mul_f32_e32 v2, v2, v178
	v_mul_f32_e32 v3, v3, v178
	v_mul_f32_e32 v4, v4, v178
	v_mul_f32_e32 v5, v5, v178
	v_mul_f32_e32 v6, v6, v178
	v_mul_f32_e32 v7, v7, v178
	v_mul_f32_e32 v8, v8, v178
	v_mul_f32_e32 v9, v9, v178
	v_mul_f32_e32 v10, v10, v178
	v_mul_f32_e32 v11, v11, v178
	v_mul_f32_e32 v12, v12, v178
	v_mul_f32_e32 v13, v13, v178
	v_mul_f32_e32 v14, v14, v178
	v_mul_f32_e32 v15, v15, v178
	v_mul_f32_e32 v16, v16, v178
	v_mul_f32_e32 v17, v17, v178
	v_mul_f32_e32 v18, v18, v178
	v_mul_f32_e32 v19, v19, v178
	v_mul_f32_e32 v20, v20, v178
	v_mul_f32_e32 v21, v21, v178
	v_mul_f32_e32 v22, v22, v178
	v_mul_f32_e32 v23, v23, v178
	v_mul_f32_e32 v24, v24, v178
	v_mul_f32_e32 v25, v25, v178
	v_mul_f32_e32 v26, v26, v178
	v_mul_f32_e32 v27, v27, v178
	v_mul_f32_e32 v28, v28, v178
	v_mul_f32_e32 v29, v29, v178
	v_mul_f32_e32 v30, v30, v178
	v_mul_f32_e32 v31, v31, v178
	v_mul_f32_e32 v218, 0xc0b17218, v168
	v_mov_b32_e32 v219, v218
	v_mov_b32_e32 v220, v218
	v_mov_b32_e32 v221, v218
	v_mov_b32_e32 v222, v218
	v_mov_b32_e32 v223, v218
	v_mov_b32_e32 v224, v218
	v_mov_b32_e32 v225, v218
	v_mov_b32_e32 v226, v218
	v_mov_b32_e32 v227, v218
	v_mov_b32_e32 v228, v218
	v_mov_b32_e32 v229, v218
	v_mov_b32_e32 v230, v218
	v_mov_b32_e32 v231, v218
	v_mov_b32_e32 v232, v218
	v_mov_b32_e32 v233, v218
.Lm0_nr_cB:
.Lm0_doneB:
	s_add_i32 s24, s47, 2
	s_cmp_ge_i32 s24, s38
	s_cbranch_scc1 .Lm0_nwB
	s_waitcnt vmcnt(3)
	ds_write_b128 v171, v[120:123]
	s_waitcnt vmcnt(2)
	ds_write_b128 v172, v[124:127] offset:26624
.Lm0_nwB:
	s_waitcnt lgkmcnt(0)
	s_barrier
	v_add_u32_e32 v177, 0xf8, v177
	s_add_i32 s47, s47, 2
	s_cmp_ge_i32 s47, s38
	s_cbranch_scc0 .LBB0_878
	s_branch .LBB0_858
